# combined + the two MFMA blocks of a segment interleaved so 4 consecutive accumulator pairs keep the same A operand
# baseline (speedup 1.0000x reference)
.LBB0_120:
	s_add_u32 s28, s40, 0xfff80080
	s_addc_u32 s29, s41, -1
	s_add_i32 s54, 0, 0x10000
	s_cmp_eq_u32 s53, 28
	s_cselect_b32 s29, s23, s29
	s_cselect_b32 s28, s22, s28
	s_cselect_b32 s43, s21, s52
	s_cselect_b32 s42, s50, s51
	s_add_i32 s56, 0, 0x14000
	v_add_u32_e32 v142, s54, v212
	v_add_u32_e32 v158, s56, v212
	ds_read_b128 v[130:133], v142
	ds_read_b128 v[134:137], v142 offset:1024
	ds_read_b128 v[138:141], v142 offset:2048
	ds_read_b128 v[142:145], v142 offset:3072
	ds_read_b128 v[146:149], v158
	ds_read_b128 v[150:153], v158 offset:1024
	ds_read_b128 v[154:157], v158 offset:2048
	ds_read_b128 v[158:161], v158 offset:3072
	s_add_i32 m0, s24, 0xc000
	ds_read_b128 v[162:165], v213
	ds_read_b128 v[166:169], v213 offset:1024
	ds_read_b128 v[170:173], v213 offset:2048
	ds_read_b128 v[174:177], v213 offset:3072
	ds_read_b128 v[188:191], v213 offset:4096
	ds_read_b128 v[192:195], v213 offset:5120
	ds_read_b128 v[196:199], v213 offset:6144
	ds_read_b128 v[200:203], v213 offset:7168
	global_load_lds_dwordx4 v184, s[40:41]
	s_add_i32 m0, s24, 0xe000
	s_nop 0
	global_load_lds_dwordx4 v186, s[40:41]
	s_waitcnt vmcnt(8)
	s_waitcnt lgkmcnt(0)
	s_barrier
	s_setprio 1
	v_mfma_f32_16x16x32_bf16 v[126:129], v[130:133], v[162:165], v[126:129]
	v_mfma_f32_16x16x32_bf16 v[126:129], v[134:137], v[166:169], v[126:129]
	v_mfma_f32_16x16x32_bf16 v[122:125], v[142:145], v[166:169], v[122:125]
	v_mfma_f32_16x16x32_bf16 v[122:125], v[138:141], v[162:165], v[122:125]
	v_mfma_f32_16x16x32_bf16 v[118:121], v[146:149], v[162:165], v[118:121]
	v_mfma_f32_16x16x32_bf16 v[118:121], v[150:153], v[166:169], v[118:121]
	v_mfma_f32_16x16x32_bf16 v[114:117], v[158:161], v[166:169], v[114:117]
	v_mfma_f32_16x16x32_bf16 v[114:117], v[154:157], v[162:165], v[114:117]
	v_mfma_f32_16x16x32_bf16 v[98:101], v[154:157], v[170:173], v[98:101]
	v_mfma_f32_16x16x32_bf16 v[98:101], v[158:161], v[174:177], v[98:101]
	v_mfma_f32_16x16x32_bf16 v[106:109], v[142:145], v[174:177], v[106:109]
	v_mfma_f32_16x16x32_bf16 v[106:109], v[138:141], v[170:173], v[106:109]
	v_mfma_f32_16x16x32_bf16 v[110:113], v[130:133], v[170:173], v[110:113]
	v_mfma_f32_16x16x32_bf16 v[110:113], v[134:137], v[174:177], v[110:113]
	v_mfma_f32_16x16x32_bf16 v[102:105], v[150:153], v[174:177], v[102:105]
	v_mfma_f32_16x16x32_bf16 v[102:105], v[146:149], v[170:173], v[102:105]
	v_mfma_f32_16x16x32_bf16 v[86:89], v[146:149], v[188:191], v[86:89]
	v_mfma_f32_16x16x32_bf16 v[86:89], v[150:153], v[192:195], v[86:89]
	v_mfma_f32_16x16x32_bf16 v[94:97], v[134:137], v[192:195], v[94:97]
	v_mfma_f32_16x16x32_bf16 v[94:97], v[130:133], v[188:191], v[94:97]
	v_mfma_f32_16x16x32_bf16 v[90:93], v[138:141], v[188:191], v[90:93]
	v_mfma_f32_16x16x32_bf16 v[90:93], v[142:145], v[192:195], v[90:93]
	v_mfma_f32_16x16x32_bf16 v[82:85], v[158:161], v[192:195], v[82:85]
	v_mfma_f32_16x16x32_bf16 v[82:85], v[154:157], v[188:191], v[82:85]
	v_mfma_f32_16x16x32_bf16 v[66:69], v[154:157], v[196:199], v[66:69]
	v_mfma_f32_16x16x32_bf16 v[66:69], v[158:161], v[200:203], v[66:69]
	v_mfma_f32_16x16x32_bf16 v[74:77], v[142:145], v[200:203], v[74:77]
	v_mfma_f32_16x16x32_bf16 v[74:77], v[138:141], v[196:199], v[74:77]
	v_mfma_f32_16x16x32_bf16 v[78:81], v[130:133], v[196:199], v[78:81]
	v_mfma_f32_16x16x32_bf16 v[78:81], v[134:137], v[200:203], v[78:81]
	v_mfma_f32_16x16x32_bf16 v[70:73], v[150:153], v[200:203], v[70:73]
	v_mfma_f32_16x16x32_bf16 v[70:73], v[146:149], v[196:199], v[70:73]
	s_setprio 0
	s_barrier
	s_add_i32 s54, s54, s1
	v_lshl_add_u64 v[204:205], s[42:43], 0, v[32:33]
	s_mov_b32 m0, s54
	ds_read_b128 v[162:165], v213 offset:16384
	ds_read_b128 v[166:169], v213 offset:17408
	ds_read_b128 v[170:173], v213 offset:18432
	ds_read_b128 v[174:177], v213 offset:19456
	ds_read_b128 v[188:191], v213 offset:20480
	ds_read_b128 v[192:195], v213 offset:21504
	ds_read_b128 v[196:199], v213 offset:22528
	ds_read_b128 v[200:203], v213 offset:23552
	global_load_lds_dwordx4 v[204:205], off
	s_add_i32 m0, s54, 0x2000
	s_add_u32 s54, s42, 0x80000
	v_lshl_add_u64 v[206:207], s[42:43], 0, v[182:183]
	s_addc_u32 s55, s43, 0
	s_add_i32 s56, s56, s1
	global_load_lds_dwordx4 v[206:207], off
	s_mov_b32 m0, s56
	v_lshl_add_u64 v[214:215], s[28:29], 0, v[180:181]
	global_load_lds_dwordx4 v32, s[54:55]
	s_add_i32 m0, s56, 0x2000
	s_nop 0
	global_load_lds_dwordx4 v182, s[54:55]
	v_lshl_add_u64 v[208:209], s[28:29], 0, v[178:179]
	s_mov_b32 m0, s24
	s_nop 0
	global_load_lds_dwordx4 v[208:209], off
	s_mov_b32 m0, s25
	s_nop 0
	global_load_lds_dwordx4 v[214:215], off
	s_waitcnt vmcnt(8)
	s_waitcnt lgkmcnt(0)
	s_barrier
	s_setprio 1
	v_mfma_f32_16x16x32_bf16 v[62:65], v[130:133], v[162:165], v[62:65]
	v_mfma_f32_16x16x32_bf16 v[62:65], v[134:137], v[166:169], v[62:65]
	v_mfma_f32_16x16x32_bf16 v[58:61], v[142:145], v[166:169], v[58:61]
	v_mfma_f32_16x16x32_bf16 v[58:61], v[138:141], v[162:165], v[58:61]
	v_mfma_f32_16x16x32_bf16 v[54:57], v[146:149], v[162:165], v[54:57]
	v_mfma_f32_16x16x32_bf16 v[54:57], v[150:153], v[166:169], v[54:57]
	v_mfma_f32_16x16x32_bf16 v[50:53], v[158:161], v[166:169], v[50:53]
	v_mfma_f32_16x16x32_bf16 v[50:53], v[154:157], v[162:165], v[50:53]
	v_mfma_f32_16x16x32_bf16 v[34:37], v[154:157], v[170:173], v[34:37]
	v_mfma_f32_16x16x32_bf16 v[34:37], v[158:161], v[174:177], v[34:37]
	v_mfma_f32_16x16x32_bf16 v[42:45], v[142:145], v[174:177], v[42:45]
	v_mfma_f32_16x16x32_bf16 v[42:45], v[138:141], v[170:173], v[42:45]
	v_mfma_f32_16x16x32_bf16 v[46:49], v[130:133], v[170:173], v[46:49]
	v_mfma_f32_16x16x32_bf16 v[46:49], v[134:137], v[174:177], v[46:49]
	v_mfma_f32_16x16x32_bf16 v[38:41], v[150:153], v[174:177], v[38:41]
	v_mfma_f32_16x16x32_bf16 v[38:41], v[146:149], v[170:173], v[38:41]
	v_mfma_f32_16x16x32_bf16 v[20:23], v[146:149], v[188:191], v[20:23]
	v_mfma_f32_16x16x32_bf16 v[20:23], v[150:153], v[192:195], v[20:23]
	v_mfma_f32_16x16x32_bf16 v[28:31], v[134:137], v[192:195], v[28:31]
	v_mfma_f32_16x16x32_bf16 v[28:31], v[130:133], v[188:191], v[28:31]
	v_mfma_f32_16x16x32_bf16 v[24:27], v[138:141], v[188:191], v[24:27]
	v_mfma_f32_16x16x32_bf16 v[24:27], v[142:145], v[192:195], v[24:27]
	v_mfma_f32_16x16x32_bf16 v[16:19], v[158:161], v[192:195], v[16:19]
	v_mfma_f32_16x16x32_bf16 v[16:19], v[154:157], v[188:191], v[16:19]
	v_mfma_f32_16x16x32_bf16 v[0:3], v[154:157], v[196:199], v[0:3]
	v_mfma_f32_16x16x32_bf16 v[0:3], v[158:161], v[200:203], v[0:3]
	v_mfma_f32_16x16x32_bf16 v[8:11], v[142:145], v[200:203], v[8:11]
	v_mfma_f32_16x16x32_bf16 v[8:11], v[138:141], v[196:199], v[8:11]
	v_mfma_f32_16x16x32_bf16 v[12:15], v[130:133], v[196:199], v[12:15]
	v_mfma_f32_16x16x32_bf16 v[12:15], v[134:137], v[200:203], v[12:15]
	v_mfma_f32_16x16x32_bf16 v[4:7], v[150:153], v[200:203], v[4:7]
	v_mfma_f32_16x16x32_bf16 v[4:7], v[146:149], v[196:199], v[4:7]
	s_setprio 0
	s_barrier
	s_add_i32 s54, 0, 0x18000
	s_add_i32 s55, 0, 0x1c000
	v_add_u32_e32 v142, s54, v212
	v_add_u32_e32 v158, s55, v212
	ds_read_b128 v[130:133], v142
	ds_read_b128 v[134:137], v142 offset:1024
	ds_read_b128 v[138:141], v142 offset:2048
	ds_read_b128 v[142:145], v142 offset:3072
	ds_read_b128 v[146:149], v158
	ds_read_b128 v[150:153], v158 offset:1024
	ds_read_b128 v[154:157], v158 offset:2048
	ds_read_b128 v[158:161], v158 offset:3072
	s_add_u32 s28, s28, 0x80000
	s_addc_u32 s29, s29, 0
	s_mov_b32 m0, s33
	ds_read_b128 v[162:165], v213 offset:32768
	ds_read_b128 v[166:169], v213 offset:33792
	ds_read_b128 v[170:173], v213 offset:34816
	ds_read_b128 v[174:177], v213 offset:35840
	ds_read_b128 v[188:191], v213 offset:36864
	ds_read_b128 v[192:195], v213 offset:37888
	ds_read_b128 v[196:199], v213 offset:38912
	ds_read_b128 v[200:203], v213 offset:39936
	global_load_lds_dwordx4 v178, s[28:29]
	s_mov_b32 m0, s36
	s_nop 0
	global_load_lds_dwordx4 v180, s[28:29]
	s_waitcnt vmcnt(8)
	s_waitcnt lgkmcnt(0)
	s_barrier
	s_setprio 1
	v_mfma_f32_16x16x32_bf16 v[126:129], v[130:133], v[162:165], v[126:129]
	v_mfma_f32_16x16x32_bf16 v[126:129], v[134:137], v[166:169], v[126:129]
	v_mfma_f32_16x16x32_bf16 v[122:125], v[142:145], v[166:169], v[122:125]
	v_mfma_f32_16x16x32_bf16 v[122:125], v[138:141], v[162:165], v[122:125]
	v_mfma_f32_16x16x32_bf16 v[118:121], v[146:149], v[162:165], v[118:121]
	v_mfma_f32_16x16x32_bf16 v[118:121], v[150:153], v[166:169], v[118:121]
	v_mfma_f32_16x16x32_bf16 v[114:117], v[158:161], v[166:169], v[114:117]
	v_mfma_f32_16x16x32_bf16 v[114:117], v[154:157], v[162:165], v[114:117]
	v_mfma_f32_16x16x32_bf16 v[98:101], v[154:157], v[170:173], v[98:101]
	v_mfma_f32_16x16x32_bf16 v[98:101], v[158:161], v[174:177], v[98:101]
	v_mfma_f32_16x16x32_bf16 v[106:109], v[142:145], v[174:177], v[106:109]
	v_mfma_f32_16x16x32_bf16 v[106:109], v[138:141], v[170:173], v[106:109]
	v_mfma_f32_16x16x32_bf16 v[110:113], v[130:133], v[170:173], v[110:113]
	v_mfma_f32_16x16x32_bf16 v[110:113], v[134:137], v[174:177], v[110:113]
	v_mfma_f32_16x16x32_bf16 v[102:105], v[150:153], v[174:177], v[102:105]
	v_mfma_f32_16x16x32_bf16 v[102:105], v[146:149], v[170:173], v[102:105]
	v_mfma_f32_16x16x32_bf16 v[86:89], v[146:149], v[188:191], v[86:89]
	v_mfma_f32_16x16x32_bf16 v[86:89], v[150:153], v[192:195], v[86:89]
	v_mfma_f32_16x16x32_bf16 v[94:97], v[134:137], v[192:195], v[94:97]
	v_mfma_f32_16x16x32_bf16 v[94:97], v[130:133], v[188:191], v[94:97]
	v_mfma_f32_16x16x32_bf16 v[90:93], v[138:141], v[188:191], v[90:93]
	v_mfma_f32_16x16x32_bf16 v[90:93], v[142:145], v[192:195], v[90:93]
	v_mfma_f32_16x16x32_bf16 v[82:85], v[158:161], v[192:195], v[82:85]
	v_mfma_f32_16x16x32_bf16 v[82:85], v[154:157], v[188:191], v[82:85]
	v_mfma_f32_16x16x32_bf16 v[66:69], v[154:157], v[196:199], v[66:69]
	v_mfma_f32_16x16x32_bf16 v[66:69], v[158:161], v[200:203], v[66:69]
	v_mfma_f32_16x16x32_bf16 v[74:77], v[142:145], v[200:203], v[74:77]
	v_mfma_f32_16x16x32_bf16 v[74:77], v[138:141], v[196:199], v[74:77]
	v_mfma_f32_16x16x32_bf16 v[78:81], v[130:133], v[196:199], v[78:81]
	v_mfma_f32_16x16x32_bf16 v[78:81], v[134:137], v[200:203], v[78:81]
	v_mfma_f32_16x16x32_bf16 v[70:73], v[150:153], v[200:203], v[70:73]
	v_mfma_f32_16x16x32_bf16 v[70:73], v[146:149], v[196:199], v[70:73]
	s_setprio 0
	s_barrier
	s_add_i32 s28, s54, s1
	v_lshl_add_u64 v[204:205], v[204:205], 0, s[34:35]
	s_mov_b32 m0, s28
	ds_read_b128 v[162:165], v213 offset:49152
	ds_read_b128 v[166:169], v213 offset:50176
	ds_read_b128 v[170:173], v213 offset:51200
	ds_read_b128 v[174:177], v213 offset:52224
	ds_read_b128 v[188:191], v213 offset:53248
	ds_read_b128 v[192:195], v213 offset:54272
	ds_read_b128 v[196:199], v213 offset:55296
	ds_read_b128 v[200:203], v213 offset:56320
	global_load_lds_dwordx4 v[204:205], off
	s_add_i32 m0, s28, 0x2000
	s_add_u32 s28, s42, 0x80080
	v_lshl_add_u64 v[204:205], v[206:207], 0, s[34:35]
	s_addc_u32 s29, s43, 0
	s_add_i32 s42, s55, s1
	global_load_lds_dwordx4 v[204:205], off
	s_mov_b32 m0, s42
	s_nop 0
	global_load_lds_dwordx4 v32, s[28:29]
	s_add_i32 m0, s42, 0x2000
	s_nop 0
	global_load_lds_dwordx4 v182, s[28:29]
	v_lshl_add_u64 v[204:205], v[208:209], 0, s[34:35]
	s_mov_b32 m0, s44
	s_nop 0
	global_load_lds_dwordx4 v[204:205], off
	v_lshl_add_u64 v[204:205], v[214:215], 0, s[34:35]
	s_mov_b32 m0, s45
	s_nop 0
	global_load_lds_dwordx4 v[204:205], off
	s_waitcnt vmcnt(8)
	s_waitcnt lgkmcnt(0)
	s_barrier
	s_setprio 1
	v_mfma_f32_16x16x32_bf16 v[62:65], v[130:133], v[162:165], v[62:65]
	v_mfma_f32_16x16x32_bf16 v[62:65], v[134:137], v[166:169], v[62:65]
	v_mfma_f32_16x16x32_bf16 v[58:61], v[142:145], v[166:169], v[58:61]
	v_mfma_f32_16x16x32_bf16 v[58:61], v[138:141], v[162:165], v[58:61]
	v_mfma_f32_16x16x32_bf16 v[54:57], v[146:149], v[162:165], v[54:57]
	v_mfma_f32_16x16x32_bf16 v[54:57], v[150:153], v[166:169], v[54:57]
	v_mfma_f32_16x16x32_bf16 v[50:53], v[158:161], v[166:169], v[50:53]
	v_mfma_f32_16x16x32_bf16 v[50:53], v[154:157], v[162:165], v[50:53]
	v_mfma_f32_16x16x32_bf16 v[34:37], v[154:157], v[170:173], v[34:37]
	v_mfma_f32_16x16x32_bf16 v[34:37], v[158:161], v[174:177], v[34:37]
	v_mfma_f32_16x16x32_bf16 v[42:45], v[142:145], v[174:177], v[42:45]
	v_mfma_f32_16x16x32_bf16 v[42:45], v[138:141], v[170:173], v[42:45]
	v_mfma_f32_16x16x32_bf16 v[46:49], v[130:133], v[170:173], v[46:49]
	v_mfma_f32_16x16x32_bf16 v[46:49], v[134:137], v[174:177], v[46:49]
	v_mfma_f32_16x16x32_bf16 v[38:41], v[150:153], v[174:177], v[38:41]
	v_mfma_f32_16x16x32_bf16 v[38:41], v[146:149], v[170:173], v[38:41]
	v_mfma_f32_16x16x32_bf16 v[20:23], v[146:149], v[188:191], v[20:23]
	v_mfma_f32_16x16x32_bf16 v[20:23], v[150:153], v[192:195], v[20:23]
	v_mfma_f32_16x16x32_bf16 v[28:31], v[134:137], v[192:195], v[28:31]
	v_mfma_f32_16x16x32_bf16 v[28:31], v[130:133], v[188:191], v[28:31]
	v_mfma_f32_16x16x32_bf16 v[24:27], v[138:141], v[188:191], v[24:27]
	v_mfma_f32_16x16x32_bf16 v[24:27], v[142:145], v[192:195], v[24:27]
	v_mfma_f32_16x16x32_bf16 v[16:19], v[158:161], v[192:195], v[16:19]
	v_mfma_f32_16x16x32_bf16 v[16:19], v[154:157], v[188:191], v[16:19]
	v_mfma_f32_16x16x32_bf16 v[0:3], v[154:157], v[196:199], v[0:3]
	v_mfma_f32_16x16x32_bf16 v[0:3], v[158:161], v[200:203], v[0:3]
	v_mfma_f32_16x16x32_bf16 v[8:11], v[142:145], v[200:203], v[8:11]
	v_mfma_f32_16x16x32_bf16 v[8:11], v[138:141], v[196:199], v[8:11]
	v_mfma_f32_16x16x32_bf16 v[12:15], v[130:133], v[196:199], v[12:15]
	v_mfma_f32_16x16x32_bf16 v[12:15], v[134:137], v[200:203], v[12:15]
	v_mfma_f32_16x16x32_bf16 v[4:7], v[150:153], v[200:203], v[4:7]
	v_mfma_f32_16x16x32_bf16 v[4:7], v[146:149], v[196:199], v[4:7]
	s_setprio 0
	s_barrier
	s_add_i32 s53, s53, 2
	s_add_u32 s40, s40, 0x100
	s_addc_u32 s41, s41, 0
	s_add_u32 s51, s51, 0x100
	s_addc_u32 s52, s52, 0
	s_cmp_gt_u32 s53, 29
	s_cbranch_scc0 .LBB0_120
	s_and_b64 vcc, exec, s[18:19]
	s_cbranch_vccz .LBB0_123
	s_barrier

.LBB0_685:
	s_add_u32 s28, s16, s40
	s_addc_u32 s29, s17, s41
	s_add_u32 s28, s28, 0x100
	s_addc_u32 s29, s29, 0
	s_add_u32 s42, s52, s40
	s_addc_u32 s43, s53, s41
	s_add_i32 s56, 0, 0x10000
	s_cmpk_eq_i32 s40, 0xf00
	s_cselect_b32 s29, s39, s29
	s_cselect_b32 s28, s38, s28
	s_cselect_b32 s43, s23, s43
	s_cselect_b32 s42, s54, s42
	s_add_i32 s58, 0, 0x14000
	v_add_u32_e32 v146, s56, v190
	v_add_u32_e32 v162, s58, v190
	ds_read_b128 v[134:137], v146
	ds_read_b128 v[138:141], v146 offset:1024
	ds_read_b128 v[142:145], v146 offset:2048
	ds_read_b128 v[146:149], v146 offset:3072
	ds_read_b128 v[150:153], v162
	ds_read_b128 v[154:157], v162 offset:1024
	ds_read_b128 v[158:161], v162 offset:2048
	ds_read_b128 v[162:165], v162 offset:3072
	v_lshl_add_u64 v[212:213], v[130:131], 0, s[40:41]
	s_add_i32 m0, s24, 0xc000
	ds_read_b128 v[166:169], v191
	ds_read_b128 v[180:183], v191 offset:1024
	ds_read_b128 v[184:187], v191 offset:2048
	ds_read_b128 v[192:195], v191 offset:3072
	ds_read_b128 v[196:199], v191 offset:4096
	ds_read_b128 v[200:203], v191 offset:5120
	ds_read_b128 v[204:207], v191 offset:6144
	ds_read_b128 v[208:211], v191 offset:7168
	global_load_lds_dwordx4 v[212:213], off
	v_lshl_add_u64 v[212:213], v[132:133], 0, s[40:41]
	s_add_i32 m0, s24, 0xe000
	s_nop 0
	global_load_lds_dwordx4 v[212:213], off
	s_waitcnt vmcnt(8)
	s_waitcnt lgkmcnt(0)
	s_barrier
	s_setprio 1
	v_mfma_f32_16x16x32_bf16 v[82:85], v[134:137], v[166:169], v[82:85]
	v_mfma_f32_16x16x32_bf16 v[82:85], v[138:141], v[180:183], v[82:85]
	v_mfma_f32_16x16x32_bf16 v[78:81], v[146:149], v[180:183], v[78:81]
	v_mfma_f32_16x16x32_bf16 v[78:81], v[142:145], v[166:169], v[78:81]
	v_mfma_f32_16x16x32_bf16 v[50:53], v[150:153], v[166:169], v[50:53]
	v_mfma_f32_16x16x32_bf16 v[50:53], v[154:157], v[180:183], v[50:53]
	v_mfma_f32_16x16x32_bf16 v[46:49], v[162:165], v[180:183], v[46:49]
	v_mfma_f32_16x16x32_bf16 v[46:49], v[158:161], v[166:169], v[46:49]
	v_mfma_f32_16x16x32_bf16 v[38:41], v[158:161], v[184:187], v[38:41]
	v_mfma_f32_16x16x32_bf16 v[38:41], v[162:165], v[192:195], v[38:41]
	v_mfma_f32_16x16x32_bf16 v[70:73], v[146:149], v[192:195], v[70:73]
	v_mfma_f32_16x16x32_bf16 v[70:73], v[142:145], v[184:187], v[70:73]
	v_mfma_f32_16x16x32_bf16 v[74:77], v[134:137], v[184:187], v[74:77]
	v_mfma_f32_16x16x32_bf16 v[74:77], v[138:141], v[192:195], v[74:77]
	v_mfma_f32_16x16x32_bf16 v[42:45], v[154:157], v[192:195], v[42:45]
	v_mfma_f32_16x16x32_bf16 v[42:45], v[150:153], v[184:187], v[42:45]
	v_mfma_f32_16x16x32_bf16 v[34:37], v[150:153], v[196:199], v[34:37]
	v_mfma_f32_16x16x32_bf16 v[34:37], v[154:157], v[200:203], v[34:37]
	v_mfma_f32_16x16x32_bf16 v[66:69], v[138:141], v[200:203], v[66:69]
	v_mfma_f32_16x16x32_bf16 v[66:69], v[134:137], v[196:199], v[66:69]
	v_mfma_f32_16x16x32_bf16 v[62:65], v[142:145], v[196:199], v[62:65]
	v_mfma_f32_16x16x32_bf16 v[62:65], v[146:149], v[200:203], v[62:65]
	v_mfma_f32_16x16x32_bf16 v[28:31], v[162:165], v[200:203], v[28:31]
	v_mfma_f32_16x16x32_bf16 v[28:31], v[158:161], v[196:199], v[28:31]
	v_mfma_f32_16x16x32_bf16 v[20:23], v[158:161], v[204:207], v[20:23]
	v_mfma_f32_16x16x32_bf16 v[20:23], v[162:165], v[208:211], v[20:23]
	v_mfma_f32_16x16x32_bf16 v[54:57], v[146:149], v[208:211], v[54:57]
	v_mfma_f32_16x16x32_bf16 v[54:57], v[142:145], v[204:207], v[54:57]
	v_mfma_f32_16x16x32_bf16 v[58:61], v[134:137], v[204:207], v[58:61]
	v_mfma_f32_16x16x32_bf16 v[58:61], v[138:141], v[208:211], v[58:61]
	v_mfma_f32_16x16x32_bf16 v[24:27], v[154:157], v[208:211], v[24:27]
	v_mfma_f32_16x16x32_bf16 v[24:27], v[150:153], v[204:207], v[24:27]
	s_setprio 0
	s_barrier
	s_add_i32 s56, s56, s13
	v_lshl_add_u64 v[212:213], s[42:43], 0, v[32:33]
	s_mov_b32 m0, s56
	ds_read_b128 v[166:169], v191 offset:16384
	ds_read_b128 v[180:183], v191 offset:17408
	ds_read_b128 v[184:187], v191 offset:18432
	ds_read_b128 v[192:195], v191 offset:19456
	ds_read_b128 v[196:199], v191 offset:20480
	ds_read_b128 v[200:203], v191 offset:21504
	ds_read_b128 v[204:207], v191 offset:22528
	ds_read_b128 v[208:211], v191 offset:23552
	global_load_lds_dwordx4 v[212:213], off
	s_add_i32 m0, s56, 0x2000
	s_add_u32 s56, s42, 0x80000
	v_lshl_add_u64 v[214:215], s[42:43], 0, v[174:175]
	s_addc_u32 s57, s43, 0
	s_add_i32 s58, s58, s13
	global_load_lds_dwordx4 v[214:215], off
	s_mov_b32 m0, s58
	v_lshl_add_u64 v[220:221], s[28:29], 0, v[172:173]
	global_load_lds_dwordx4 v32, s[56:57]
	s_add_i32 m0, s58, 0x2000
	s_nop 0
	global_load_lds_dwordx4 v174, s[56:57]
	v_lshl_add_u64 v[216:217], s[28:29], 0, v[170:171]
	s_mov_b32 m0, s24
	s_nop 0
	global_load_lds_dwordx4 v[216:217], off
	s_mov_b32 m0, s25
	s_nop 0
	global_load_lds_dwordx4 v[220:221], off
	s_waitcnt vmcnt(8)
	s_waitcnt lgkmcnt(0)
	s_barrier
	s_setprio 1
	v_mfma_f32_16x16x32_bf16 v[16:19], v[134:137], v[166:169], v[16:19]
	v_mfma_f32_16x16x32_bf16 v[16:19], v[138:141], v[180:183], v[16:19]
	v_mfma_f32_16x16x32_bf16 v[12:15], v[146:149], v[180:183], v[12:15]
	v_mfma_f32_16x16x32_bf16 v[12:15], v[142:145], v[166:169], v[12:15]
	v_mfma_f32_16x16x32_bf16 v[98:101], v[150:153], v[166:169], v[98:101]
	v_mfma_f32_16x16x32_bf16 v[98:101], v[154:157], v[180:183], v[98:101]
	v_mfma_f32_16x16x32_bf16 v[102:105], v[162:165], v[180:183], v[102:105]
	v_mfma_f32_16x16x32_bf16 v[102:105], v[158:161], v[166:169], v[102:105]
	v_mfma_f32_16x16x32_bf16 v[110:113], v[158:161], v[184:187], v[110:113]
	v_mfma_f32_16x16x32_bf16 v[110:113], v[162:165], v[192:195], v[110:113]
	v_mfma_f32_16x16x32_bf16 v[4:7], v[146:149], v[192:195], v[4:7]
	v_mfma_f32_16x16x32_bf16 v[4:7], v[142:145], v[184:187], v[4:7]
	v_mfma_f32_16x16x32_bf16 v[8:11], v[134:137], v[184:187], v[8:11]
	v_mfma_f32_16x16x32_bf16 v[8:11], v[138:141], v[192:195], v[8:11]
	v_mfma_f32_16x16x32_bf16 v[106:109], v[154:157], v[192:195], v[106:109]
	v_mfma_f32_16x16x32_bf16 v[106:109], v[150:153], v[184:187], v[106:109]
	v_mfma_f32_16x16x32_bf16 v[114:117], v[150:153], v[196:199], v[114:117]
	v_mfma_f32_16x16x32_bf16 v[114:117], v[154:157], v[200:203], v[114:117]
	v_mfma_f32_16x16x32_bf16 v[0:3], v[138:141], v[200:203], v[0:3]
	v_mfma_f32_16x16x32_bf16 v[0:3], v[134:137], v[196:199], v[0:3]
	v_mfma_f32_16x16x32_bf16 v[86:89], v[142:145], v[196:199], v[86:89]
	v_mfma_f32_16x16x32_bf16 v[86:89], v[146:149], v[200:203], v[86:89]
	v_mfma_f32_16x16x32_bf16 v[118:121], v[162:165], v[200:203], v[118:121]
	v_mfma_f32_16x16x32_bf16 v[118:121], v[158:161], v[196:199], v[118:121]
	v_mfma_f32_16x16x32_bf16 v[126:129], v[158:161], v[204:207], v[126:129]
	v_mfma_f32_16x16x32_bf16 v[126:129], v[162:165], v[208:211], v[126:129]
	v_mfma_f32_16x16x32_bf16 v[94:97], v[146:149], v[208:211], v[94:97]
	v_mfma_f32_16x16x32_bf16 v[94:97], v[142:145], v[204:207], v[94:97]
	v_mfma_f32_16x16x32_bf16 v[90:93], v[134:137], v[204:207], v[90:93]
	v_mfma_f32_16x16x32_bf16 v[90:93], v[138:141], v[208:211], v[90:93]
	v_mfma_f32_16x16x32_bf16 v[122:125], v[154:157], v[208:211], v[122:125]
	v_mfma_f32_16x16x32_bf16 v[122:125], v[150:153], v[204:207], v[122:125]
	s_setprio 0
	s_barrier
	s_add_i32 s56, 0, 0x18000
	s_add_i32 s57, 0, 0x1c000
	v_add_u32_e32 v146, s56, v190
	v_add_u32_e32 v162, s57, v190
	ds_read_b128 v[134:137], v146
	ds_read_b128 v[138:141], v146 offset:1024
	ds_read_b128 v[142:145], v146 offset:2048
	ds_read_b128 v[146:149], v146 offset:3072
	ds_read_b128 v[150:153], v162
	ds_read_b128 v[154:157], v162 offset:1024
	ds_read_b128 v[158:161], v162 offset:2048
	ds_read_b128 v[162:165], v162 offset:3072
	s_add_u32 s28, s28, 0x80000
	s_addc_u32 s29, s29, 0
	s_mov_b32 m0, s33
	ds_read_b128 v[166:169], v191 offset:32768
	ds_read_b128 v[180:183], v191 offset:33792
	ds_read_b128 v[184:187], v191 offset:34816
	ds_read_b128 v[192:195], v191 offset:35840
	ds_read_b128 v[196:199], v191 offset:36864
	ds_read_b128 v[200:203], v191 offset:37888
	ds_read_b128 v[204:207], v191 offset:38912
	ds_read_b128 v[208:211], v191 offset:39936
	global_load_lds_dwordx4 v170, s[28:29]
	s_mov_b32 m0, s36
	s_nop 0
	global_load_lds_dwordx4 v172, s[28:29]
	s_waitcnt vmcnt(8)
	s_waitcnt lgkmcnt(0)
	s_barrier
	s_setprio 1
	v_mfma_f32_16x16x32_bf16 v[82:85], v[134:137], v[166:169], v[82:85]
	v_mfma_f32_16x16x32_bf16 v[82:85], v[138:141], v[180:183], v[82:85]
	v_mfma_f32_16x16x32_bf16 v[78:81], v[146:149], v[180:183], v[78:81]
	v_mfma_f32_16x16x32_bf16 v[78:81], v[142:145], v[166:169], v[78:81]
	v_mfma_f32_16x16x32_bf16 v[50:53], v[150:153], v[166:169], v[50:53]
	v_mfma_f32_16x16x32_bf16 v[50:53], v[154:157], v[180:183], v[50:53]
	v_mfma_f32_16x16x32_bf16 v[46:49], v[162:165], v[180:183], v[46:49]
	v_mfma_f32_16x16x32_bf16 v[46:49], v[158:161], v[166:169], v[46:49]
	v_mfma_f32_16x16x32_bf16 v[38:41], v[158:161], v[184:187], v[38:41]
	v_mfma_f32_16x16x32_bf16 v[38:41], v[162:165], v[192:195], v[38:41]
	v_mfma_f32_16x16x32_bf16 v[70:73], v[146:149], v[192:195], v[70:73]
	v_mfma_f32_16x16x32_bf16 v[70:73], v[142:145], v[184:187], v[70:73]
	v_mfma_f32_16x16x32_bf16 v[74:77], v[134:137], v[184:187], v[74:77]
	v_mfma_f32_16x16x32_bf16 v[74:77], v[138:141], v[192:195], v[74:77]
	v_mfma_f32_16x16x32_bf16 v[42:45], v[154:157], v[192:195], v[42:45]
	v_mfma_f32_16x16x32_bf16 v[42:45], v[150:153], v[184:187], v[42:45]
	v_mfma_f32_16x16x32_bf16 v[34:37], v[150:153], v[196:199], v[34:37]
	v_mfma_f32_16x16x32_bf16 v[34:37], v[154:157], v[200:203], v[34:37]
	v_mfma_f32_16x16x32_bf16 v[66:69], v[138:141], v[200:203], v[66:69]
	v_mfma_f32_16x16x32_bf16 v[66:69], v[134:137], v[196:199], v[66:69]
	v_mfma_f32_16x16x32_bf16 v[62:65], v[142:145], v[196:199], v[62:65]
	v_mfma_f32_16x16x32_bf16 v[62:65], v[146:149], v[200:203], v[62:65]
	v_mfma_f32_16x16x32_bf16 v[28:31], v[162:165], v[200:203], v[28:31]
	v_mfma_f32_16x16x32_bf16 v[28:31], v[158:161], v[196:199], v[28:31]
	v_mfma_f32_16x16x32_bf16 v[20:23], v[158:161], v[204:207], v[20:23]
	v_mfma_f32_16x16x32_bf16 v[20:23], v[162:165], v[208:211], v[20:23]
	v_mfma_f32_16x16x32_bf16 v[54:57], v[146:149], v[208:211], v[54:57]
	v_mfma_f32_16x16x32_bf16 v[54:57], v[142:145], v[204:207], v[54:57]
	v_mfma_f32_16x16x32_bf16 v[58:61], v[134:137], v[204:207], v[58:61]
	v_mfma_f32_16x16x32_bf16 v[58:61], v[138:141], v[208:211], v[58:61]
	v_mfma_f32_16x16x32_bf16 v[24:27], v[154:157], v[208:211], v[24:27]
	v_mfma_f32_16x16x32_bf16 v[24:27], v[150:153], v[204:207], v[24:27]
	s_setprio 0
	s_barrier
	s_add_i32 s28, s56, s13
	v_lshl_add_u64 v[212:213], v[212:213], 0, s[34:35]
	s_mov_b32 m0, s28
	ds_read_b128 v[166:169], v191 offset:49152
	ds_read_b128 v[180:183], v191 offset:50176
	ds_read_b128 v[184:187], v191 offset:51200
	ds_read_b128 v[192:195], v191 offset:52224
	ds_read_b128 v[196:199], v191 offset:53248
	ds_read_b128 v[200:203], v191 offset:54272
	ds_read_b128 v[204:207], v191 offset:55296
	ds_read_b128 v[208:211], v191 offset:56320
	global_load_lds_dwordx4 v[212:213], off
	s_add_i32 m0, s28, 0x2000
	s_add_u32 s28, s42, 0x80080
	v_lshl_add_u64 v[212:213], v[214:215], 0, s[34:35]
	s_addc_u32 s29, s43, 0
	s_add_i32 s42, s57, s13
	global_load_lds_dwordx4 v[212:213], off
	s_mov_b32 m0, s42
	s_nop 0
	global_load_lds_dwordx4 v32, s[28:29]
	s_add_i32 m0, s42, 0x2000
	s_nop 0
	global_load_lds_dwordx4 v174, s[28:29]
	v_lshl_add_u64 v[212:213], v[216:217], 0, s[34:35]
	s_mov_b32 m0, s45
	s_nop 0
	global_load_lds_dwordx4 v[212:213], off
	v_lshl_add_u64 v[212:213], v[220:221], 0, s[34:35]
	s_mov_b32 m0, s46
	s_nop 0
	global_load_lds_dwordx4 v[212:213], off
	s_waitcnt vmcnt(8)
	s_waitcnt lgkmcnt(0)
	s_barrier
	s_setprio 1
	v_mfma_f32_16x16x32_bf16 v[16:19], v[134:137], v[166:169], v[16:19]
	v_mfma_f32_16x16x32_bf16 v[16:19], v[138:141], v[180:183], v[16:19]
	v_mfma_f32_16x16x32_bf16 v[12:15], v[146:149], v[180:183], v[12:15]
	v_mfma_f32_16x16x32_bf16 v[12:15], v[142:145], v[166:169], v[12:15]
	v_mfma_f32_16x16x32_bf16 v[98:101], v[150:153], v[166:169], v[98:101]
	v_mfma_f32_16x16x32_bf16 v[98:101], v[154:157], v[180:183], v[98:101]
	v_mfma_f32_16x16x32_bf16 v[102:105], v[162:165], v[180:183], v[102:105]
	v_mfma_f32_16x16x32_bf16 v[102:105], v[158:161], v[166:169], v[102:105]
	v_mfma_f32_16x16x32_bf16 v[110:113], v[158:161], v[184:187], v[110:113]
	v_mfma_f32_16x16x32_bf16 v[110:113], v[162:165], v[192:195], v[110:113]
	v_mfma_f32_16x16x32_bf16 v[4:7], v[146:149], v[192:195], v[4:7]
	v_mfma_f32_16x16x32_bf16 v[4:7], v[142:145], v[184:187], v[4:7]
	v_mfma_f32_16x16x32_bf16 v[8:11], v[134:137], v[184:187], v[8:11]
	v_mfma_f32_16x16x32_bf16 v[8:11], v[138:141], v[192:195], v[8:11]
	v_mfma_f32_16x16x32_bf16 v[106:109], v[154:157], v[192:195], v[106:109]
	v_mfma_f32_16x16x32_bf16 v[106:109], v[150:153], v[184:187], v[106:109]
	v_mfma_f32_16x16x32_bf16 v[114:117], v[150:153], v[196:199], v[114:117]
	v_mfma_f32_16x16x32_bf16 v[114:117], v[154:157], v[200:203], v[114:117]
	v_mfma_f32_16x16x32_bf16 v[0:3], v[138:141], v[200:203], v[0:3]
	v_mfma_f32_16x16x32_bf16 v[0:3], v[134:137], v[196:199], v[0:3]
	v_mfma_f32_16x16x32_bf16 v[86:89], v[142:145], v[196:199], v[86:89]
	v_mfma_f32_16x16x32_bf16 v[86:89], v[146:149], v[200:203], v[86:89]
	v_mfma_f32_16x16x32_bf16 v[118:121], v[162:165], v[200:203], v[118:121]
	v_mfma_f32_16x16x32_bf16 v[118:121], v[158:161], v[196:199], v[118:121]
	v_mfma_f32_16x16x32_bf16 v[126:129], v[158:161], v[204:207], v[126:129]
	v_mfma_f32_16x16x32_bf16 v[126:129], v[162:165], v[208:211], v[126:129]
	v_mfma_f32_16x16x32_bf16 v[94:97], v[146:149], v[208:211], v[94:97]
	v_mfma_f32_16x16x32_bf16 v[94:97], v[142:145], v[204:207], v[94:97]
	v_mfma_f32_16x16x32_bf16 v[90:93], v[134:137], v[204:207], v[90:93]
	v_mfma_f32_16x16x32_bf16 v[90:93], v[138:141], v[208:211], v[90:93]
	v_mfma_f32_16x16x32_bf16 v[122:125], v[154:157], v[208:211], v[122:125]
	v_mfma_f32_16x16x32_bf16 v[122:125], v[150:153], v[204:207], v[122:125]
	s_setprio 0
	s_barrier
	s_add_i32 s55, s55, 2
	s_add_u32 s40, s40, 0x100
	s_addc_u32 s41, s41, 0
	s_cmp_gt_u32 s55, 29
	s_cbranch_scc0 .LBB0_685
	s_and_b64 vcc, exec, s[18:19]
	s_cbranch_vccz .LBB0_688
	s_barrier

.LBB0_755:
	s_add_u32 s6, s4, 0x100
	s_addc_u32 s7, s5, 0
	s_add_i32 s52, 0, 0x10000
	s_cmpk_eq_i32 s51, 0x54
	s_cselect_b32 s29, s23, s7
	s_cselect_b32 s28, s22, s6
	s_cselect_b32 s31, s27, s50
	s_cselect_b32 s30, s26, s33
	s_add_i32 s53, 0, 0x14000
	v_add_u32_e32 v142, s52, v242
	v_add_u32_e32 v158, s53, v242
	ds_read_b128 v[130:133], v142
	ds_read_b128 v[134:137], v142 offset:1024
	ds_read_b128 v[138:141], v142 offset:2048
	ds_read_b128 v[142:145], v142 offset:3072
	ds_read_b128 v[146:149], v158
	ds_read_b128 v[150:153], v158 offset:1024
	ds_read_b128 v[154:157], v158 offset:2048
	ds_read_b128 v[158:161], v158 offset:3072
	s_add_i32 m0, s36, 0xc000
	ds_read_b128 v[162:165], v243
	ds_read_b128 v[166:169], v243 offset:1024
	ds_read_b128 v[170:173], v243 offset:2048
	ds_read_b128 v[174:177], v243 offset:3072
	ds_read_b128 v[178:181], v243 offset:4096
	ds_read_b128 v[182:185], v243 offset:5120
	ds_read_b128 v[186:189], v243 offset:6144
	ds_read_b128 v[190:193], v243 offset:7168
	global_load_lds_dwordx4 v202, s[4:5]
	s_add_i32 m0, s36, 0xe000
	s_nop 0
	global_load_lds_dwordx4 v204, s[4:5]
	s_waitcnt vmcnt(8)
	s_waitcnt lgkmcnt(0)
	s_barrier
	s_setprio 1
	v_mfma_f32_16x16x32_bf16 v[126:129], v[130:133], v[162:165], v[126:129]
	v_mfma_f32_16x16x32_bf16 v[126:129], v[134:137], v[166:169], v[126:129]
	v_mfma_f32_16x16x32_bf16 v[122:125], v[142:145], v[166:169], v[122:125]
	v_mfma_f32_16x16x32_bf16 v[122:125], v[138:141], v[162:165], v[122:125]
	v_mfma_f32_16x16x32_bf16 v[118:121], v[146:149], v[162:165], v[118:121]
	v_mfma_f32_16x16x32_bf16 v[118:121], v[150:153], v[166:169], v[118:121]
	v_mfma_f32_16x16x32_bf16 v[114:117], v[158:161], v[166:169], v[114:117]
	v_mfma_f32_16x16x32_bf16 v[114:117], v[154:157], v[162:165], v[114:117]
	v_mfma_f32_16x16x32_bf16 v[98:101], v[154:157], v[170:173], v[98:101]
	v_mfma_f32_16x16x32_bf16 v[98:101], v[158:161], v[174:177], v[98:101]
	v_mfma_f32_16x16x32_bf16 v[106:109], v[142:145], v[174:177], v[106:109]
	v_mfma_f32_16x16x32_bf16 v[106:109], v[138:141], v[170:173], v[106:109]
	v_mfma_f32_16x16x32_bf16 v[110:113], v[130:133], v[170:173], v[110:113]
	v_mfma_f32_16x16x32_bf16 v[110:113], v[134:137], v[174:177], v[110:113]
	v_mfma_f32_16x16x32_bf16 v[102:105], v[150:153], v[174:177], v[102:105]
	v_mfma_f32_16x16x32_bf16 v[102:105], v[146:149], v[170:173], v[102:105]
	v_mfma_f32_16x16x32_bf16 v[86:89], v[146:149], v[178:181], v[86:89]
	v_mfma_f32_16x16x32_bf16 v[86:89], v[150:153], v[182:185], v[86:89]
	v_mfma_f32_16x16x32_bf16 v[94:97], v[134:137], v[182:185], v[94:97]
	v_mfma_f32_16x16x32_bf16 v[94:97], v[130:133], v[178:181], v[94:97]
	v_mfma_f32_16x16x32_bf16 v[90:93], v[138:141], v[178:181], v[90:93]
	v_mfma_f32_16x16x32_bf16 v[90:93], v[142:145], v[182:185], v[90:93]
	v_mfma_f32_16x16x32_bf16 v[82:85], v[158:161], v[182:185], v[82:85]
	v_mfma_f32_16x16x32_bf16 v[82:85], v[154:157], v[178:181], v[82:85]
	v_mfma_f32_16x16x32_bf16 v[66:69], v[154:157], v[186:189], v[66:69]
	v_mfma_f32_16x16x32_bf16 v[66:69], v[158:161], v[190:193], v[66:69]
	v_mfma_f32_16x16x32_bf16 v[74:77], v[142:145], v[190:193], v[74:77]
	v_mfma_f32_16x16x32_bf16 v[74:77], v[138:141], v[186:189], v[74:77]
	v_mfma_f32_16x16x32_bf16 v[78:81], v[130:133], v[186:189], v[78:81]
	v_mfma_f32_16x16x32_bf16 v[78:81], v[134:137], v[190:193], v[78:81]
	v_mfma_f32_16x16x32_bf16 v[70:73], v[150:153], v[190:193], v[70:73]
	v_mfma_f32_16x16x32_bf16 v[70:73], v[146:149], v[186:189], v[70:73]
	s_setprio 0
	s_barrier
	s_add_i32 s4, s52, s1
	v_lshl_add_u64 v[194:195], s[30:31], 0, v[32:33]
	s_mov_b32 m0, s4
	ds_read_b128 v[162:165], v243 offset:16384
	ds_read_b128 v[166:169], v243 offset:17408
	ds_read_b128 v[170:173], v243 offset:18432
	ds_read_b128 v[174:177], v243 offset:19456
	ds_read_b128 v[178:181], v243 offset:20480
	ds_read_b128 v[182:185], v243 offset:21504
	ds_read_b128 v[186:189], v243 offset:22528
	ds_read_b128 v[190:193], v243 offset:23552
	global_load_lds_dwordx4 v[194:195], off
	s_add_i32 m0, s4, 0x2000
	s_add_u32 s4, s30, 0x160000
	v_lshl_add_u64 v[206:207], s[30:31], 0, v[200:201]
	s_addc_u32 s5, s31, 0
	s_add_i32 s52, s53, s1
	global_load_lds_dwordx4 v[206:207], off
	s_mov_b32 m0, s52
	v_lshl_add_u64 v[210:211], s[28:29], 0, v[198:199]
	global_load_lds_dwordx4 v32, s[4:5]
	s_add_i32 m0, s52, 0x2000
	s_nop 0
	global_load_lds_dwordx4 v200, s[4:5]
	v_lshl_add_u64 v[208:209], s[28:29], 0, v[196:197]
	s_mov_b32 m0, s36
	s_nop 0
	global_load_lds_dwordx4 v[208:209], off
	s_mov_b32 m0, s38
	s_nop 0
	global_load_lds_dwordx4 v[210:211], off
	s_waitcnt vmcnt(8)
	s_waitcnt lgkmcnt(0)
	s_barrier
	s_setprio 1
	v_mfma_f32_16x16x32_bf16 v[62:65], v[130:133], v[162:165], v[62:65]
	v_mfma_f32_16x16x32_bf16 v[62:65], v[134:137], v[166:169], v[62:65]
	v_mfma_f32_16x16x32_bf16 v[58:61], v[142:145], v[166:169], v[58:61]
	v_mfma_f32_16x16x32_bf16 v[58:61], v[138:141], v[162:165], v[58:61]
	v_mfma_f32_16x16x32_bf16 v[54:57], v[146:149], v[162:165], v[54:57]
	v_mfma_f32_16x16x32_bf16 v[54:57], v[150:153], v[166:169], v[54:57]
	v_mfma_f32_16x16x32_bf16 v[50:53], v[158:161], v[166:169], v[50:53]
	v_mfma_f32_16x16x32_bf16 v[50:53], v[154:157], v[162:165], v[50:53]
	v_mfma_f32_16x16x32_bf16 v[34:37], v[154:157], v[170:173], v[34:37]
	v_mfma_f32_16x16x32_bf16 v[34:37], v[158:161], v[174:177], v[34:37]
	v_mfma_f32_16x16x32_bf16 v[42:45], v[142:145], v[174:177], v[42:45]
	v_mfma_f32_16x16x32_bf16 v[42:45], v[138:141], v[170:173], v[42:45]
	v_mfma_f32_16x16x32_bf16 v[46:49], v[130:133], v[170:173], v[46:49]
	v_mfma_f32_16x16x32_bf16 v[46:49], v[134:137], v[174:177], v[46:49]
	v_mfma_f32_16x16x32_bf16 v[38:41], v[150:153], v[174:177], v[38:41]
	v_mfma_f32_16x16x32_bf16 v[38:41], v[146:149], v[170:173], v[38:41]
	v_mfma_f32_16x16x32_bf16 v[20:23], v[146:149], v[178:181], v[20:23]
	v_mfma_f32_16x16x32_bf16 v[20:23], v[150:153], v[182:185], v[20:23]
	v_mfma_f32_16x16x32_bf16 v[28:31], v[134:137], v[182:185], v[28:31]
	v_mfma_f32_16x16x32_bf16 v[28:31], v[130:133], v[178:181], v[28:31]
	v_mfma_f32_16x16x32_bf16 v[24:27], v[138:141], v[178:181], v[24:27]
	v_mfma_f32_16x16x32_bf16 v[24:27], v[142:145], v[182:185], v[24:27]
	v_mfma_f32_16x16x32_bf16 v[16:19], v[158:161], v[182:185], v[16:19]
	v_mfma_f32_16x16x32_bf16 v[16:19], v[154:157], v[178:181], v[16:19]
	v_mfma_f32_16x16x32_bf16 v[0:3], v[154:157], v[186:189], v[0:3]
	v_mfma_f32_16x16x32_bf16 v[0:3], v[158:161], v[190:193], v[0:3]
	v_mfma_f32_16x16x32_bf16 v[8:11], v[142:145], v[190:193], v[8:11]
	v_mfma_f32_16x16x32_bf16 v[8:11], v[138:141], v[186:189], v[8:11]
	v_mfma_f32_16x16x32_bf16 v[12:15], v[130:133], v[186:189], v[12:15]
	v_mfma_f32_16x16x32_bf16 v[12:15], v[134:137], v[190:193], v[12:15]
	v_mfma_f32_16x16x32_bf16 v[4:7], v[150:153], v[190:193], v[4:7]
	v_mfma_f32_16x16x32_bf16 v[4:7], v[146:149], v[186:189], v[4:7]
	s_setprio 0
	s_barrier
	s_add_i32 s52, 0, 0x18000
	s_add_i32 s53, 0, 0x1c000
	v_add_u32_e32 v142, s52, v242
	v_add_u32_e32 v158, s53, v242
	ds_read_b128 v[130:133], v142
	ds_read_b128 v[134:137], v142 offset:1024
	ds_read_b128 v[138:141], v142 offset:2048
	ds_read_b128 v[142:145], v142 offset:3072
	ds_read_b128 v[146:149], v158
	ds_read_b128 v[150:153], v158 offset:1024
	ds_read_b128 v[154:157], v158 offset:2048
	ds_read_b128 v[158:161], v158 offset:3072
	s_add_u32 s4, s28, 0x160000
	s_addc_u32 s5, s29, 0
	s_mov_b32 m0, s39
	ds_read_b128 v[162:165], v243 offset:32768
	ds_read_b128 v[166:169], v243 offset:33792
	ds_read_b128 v[170:173], v243 offset:34816
	ds_read_b128 v[174:177], v243 offset:35840
	ds_read_b128 v[178:181], v243 offset:36864
	ds_read_b128 v[182:185], v243 offset:37888
	ds_read_b128 v[186:189], v243 offset:38912
	ds_read_b128 v[190:193], v243 offset:39936
	global_load_lds_dwordx4 v196, s[4:5]
	s_mov_b32 m0, s42
	s_nop 0
	global_load_lds_dwordx4 v198, s[4:5]
	s_waitcnt vmcnt(8)
	s_waitcnt lgkmcnt(0)
	s_barrier
	s_setprio 1
	v_mfma_f32_16x16x32_bf16 v[126:129], v[130:133], v[162:165], v[126:129]
	v_mfma_f32_16x16x32_bf16 v[126:129], v[134:137], v[166:169], v[126:129]
	v_mfma_f32_16x16x32_bf16 v[122:125], v[142:145], v[166:169], v[122:125]
	v_mfma_f32_16x16x32_bf16 v[122:125], v[138:141], v[162:165], v[122:125]
	v_mfma_f32_16x16x32_bf16 v[118:121], v[146:149], v[162:165], v[118:121]
	v_mfma_f32_16x16x32_bf16 v[118:121], v[150:153], v[166:169], v[118:121]
	v_mfma_f32_16x16x32_bf16 v[114:117], v[158:161], v[166:169], v[114:117]
	v_mfma_f32_16x16x32_bf16 v[114:117], v[154:157], v[162:165], v[114:117]
	v_mfma_f32_16x16x32_bf16 v[98:101], v[154:157], v[170:173], v[98:101]
	v_mfma_f32_16x16x32_bf16 v[98:101], v[158:161], v[174:177], v[98:101]
	v_mfma_f32_16x16x32_bf16 v[106:109], v[142:145], v[174:177], v[106:109]
	v_mfma_f32_16x16x32_bf16 v[106:109], v[138:141], v[170:173], v[106:109]
	v_mfma_f32_16x16x32_bf16 v[110:113], v[130:133], v[170:173], v[110:113]
	v_mfma_f32_16x16x32_bf16 v[110:113], v[134:137], v[174:177], v[110:113]
	v_mfma_f32_16x16x32_bf16 v[102:105], v[150:153], v[174:177], v[102:105]
	v_mfma_f32_16x16x32_bf16 v[102:105], v[146:149], v[170:173], v[102:105]
	v_mfma_f32_16x16x32_bf16 v[86:89], v[146:149], v[178:181], v[86:89]
	v_mfma_f32_16x16x32_bf16 v[86:89], v[150:153], v[182:185], v[86:89]
	v_mfma_f32_16x16x32_bf16 v[94:97], v[134:137], v[182:185], v[94:97]
	v_mfma_f32_16x16x32_bf16 v[94:97], v[130:133], v[178:181], v[94:97]
	v_mfma_f32_16x16x32_bf16 v[90:93], v[138:141], v[178:181], v[90:93]
	v_mfma_f32_16x16x32_bf16 v[90:93], v[142:145], v[182:185], v[90:93]
	v_mfma_f32_16x16x32_bf16 v[82:85], v[158:161], v[182:185], v[82:85]
	v_mfma_f32_16x16x32_bf16 v[82:85], v[154:157], v[178:181], v[82:85]
	v_mfma_f32_16x16x32_bf16 v[66:69], v[154:157], v[186:189], v[66:69]
	v_mfma_f32_16x16x32_bf16 v[66:69], v[158:161], v[190:193], v[66:69]
	v_mfma_f32_16x16x32_bf16 v[74:77], v[142:145], v[190:193], v[74:77]
	v_mfma_f32_16x16x32_bf16 v[74:77], v[138:141], v[186:189], v[74:77]
	v_mfma_f32_16x16x32_bf16 v[78:81], v[130:133], v[186:189], v[78:81]
	v_mfma_f32_16x16x32_bf16 v[78:81], v[134:137], v[190:193], v[78:81]
	v_mfma_f32_16x16x32_bf16 v[70:73], v[150:153], v[190:193], v[70:73]
	v_mfma_f32_16x16x32_bf16 v[70:73], v[146:149], v[186:189], v[70:73]
	s_setprio 0
	s_barrier
	s_add_i32 s4, s52, s1
	v_lshl_add_u64 v[194:195], v[194:195], 0, s[34:35]
	s_mov_b32 m0, s4
	ds_read_b128 v[162:165], v243 offset:49152
	ds_read_b128 v[166:169], v243 offset:50176
	ds_read_b128 v[170:173], v243 offset:51200
	ds_read_b128 v[174:177], v243 offset:52224
	ds_read_b128 v[178:181], v243 offset:53248
	ds_read_b128 v[182:185], v243 offset:54272
	ds_read_b128 v[186:189], v243 offset:55296
	ds_read_b128 v[190:193], v243 offset:56320
	global_load_lds_dwordx4 v[194:195], off
	s_add_i32 m0, s4, 0x2000
	s_add_u32 s4, s30, 0x160080
	v_lshl_add_u64 v[194:195], v[206:207], 0, s[34:35]
	s_addc_u32 s5, s31, 0
	s_add_i32 s28, s53, s1
	global_load_lds_dwordx4 v[194:195], off
	s_mov_b32 m0, s28
	s_nop 0
	global_load_lds_dwordx4 v32, s[4:5]
	s_add_i32 m0, s28, 0x2000
	s_nop 0
	global_load_lds_dwordx4 v200, s[4:5]
	v_lshl_add_u64 v[194:195], v[208:209], 0, s[34:35]
	s_mov_b32 m0, s44
	s_nop 0
	global_load_lds_dwordx4 v[194:195], off
	v_lshl_add_u64 v[194:195], v[210:211], 0, s[34:35]
	s_mov_b32 m0, s45
	s_nop 0
	global_load_lds_dwordx4 v[194:195], off
	s_waitcnt vmcnt(8)
	s_waitcnt lgkmcnt(0)
	s_barrier
	s_setprio 1
	v_mfma_f32_16x16x32_bf16 v[62:65], v[130:133], v[162:165], v[62:65]
	v_mfma_f32_16x16x32_bf16 v[62:65], v[134:137], v[166:169], v[62:65]
	v_mfma_f32_16x16x32_bf16 v[58:61], v[142:145], v[166:169], v[58:61]
	v_mfma_f32_16x16x32_bf16 v[58:61], v[138:141], v[162:165], v[58:61]
	v_mfma_f32_16x16x32_bf16 v[54:57], v[146:149], v[162:165], v[54:57]
	v_mfma_f32_16x16x32_bf16 v[54:57], v[150:153], v[166:169], v[54:57]
	v_mfma_f32_16x16x32_bf16 v[50:53], v[158:161], v[166:169], v[50:53]
	v_mfma_f32_16x16x32_bf16 v[50:53], v[154:157], v[162:165], v[50:53]
	v_mfma_f32_16x16x32_bf16 v[34:37], v[154:157], v[170:173], v[34:37]
	v_mfma_f32_16x16x32_bf16 v[34:37], v[158:161], v[174:177], v[34:37]
	v_mfma_f32_16x16x32_bf16 v[42:45], v[142:145], v[174:177], v[42:45]
	v_mfma_f32_16x16x32_bf16 v[42:45], v[138:141], v[170:173], v[42:45]
	v_mfma_f32_16x16x32_bf16 v[46:49], v[130:133], v[170:173], v[46:49]
	v_mfma_f32_16x16x32_bf16 v[46:49], v[134:137], v[174:177], v[46:49]
	v_mfma_f32_16x16x32_bf16 v[38:41], v[150:153], v[174:177], v[38:41]
	v_mfma_f32_16x16x32_bf16 v[38:41], v[146:149], v[170:173], v[38:41]
	v_mfma_f32_16x16x32_bf16 v[20:23], v[146:149], v[178:181], v[20:23]
	v_mfma_f32_16x16x32_bf16 v[20:23], v[150:153], v[182:185], v[20:23]
	v_mfma_f32_16x16x32_bf16 v[28:31], v[134:137], v[182:185], v[28:31]
	v_mfma_f32_16x16x32_bf16 v[28:31], v[130:133], v[178:181], v[28:31]
	v_mfma_f32_16x16x32_bf16 v[24:27], v[138:141], v[178:181], v[24:27]
	v_mfma_f32_16x16x32_bf16 v[24:27], v[142:145], v[182:185], v[24:27]
	v_mfma_f32_16x16x32_bf16 v[16:19], v[158:161], v[182:185], v[16:19]
	v_mfma_f32_16x16x32_bf16 v[16:19], v[154:157], v[178:181], v[16:19]
	v_mfma_f32_16x16x32_bf16 v[0:3], v[154:157], v[186:189], v[0:3]
	v_mfma_f32_16x16x32_bf16 v[0:3], v[158:161], v[190:193], v[0:3]
	v_mfma_f32_16x16x32_bf16 v[8:11], v[142:145], v[190:193], v[8:11]
	v_mfma_f32_16x16x32_bf16 v[8:11], v[138:141], v[186:189], v[8:11]
	v_mfma_f32_16x16x32_bf16 v[12:15], v[130:133], v[186:189], v[12:15]
	v_mfma_f32_16x16x32_bf16 v[12:15], v[134:137], v[190:193], v[12:15]
	v_mfma_f32_16x16x32_bf16 v[4:7], v[150:153], v[190:193], v[4:7]
	v_mfma_f32_16x16x32_bf16 v[4:7], v[146:149], v[186:189], v[4:7]
	s_setprio 0
	s_barrier
	s_add_i32 s51, s51, 2
	s_add_u32 s33, s33, 0x100
	s_addc_u32 s50, s50, 0
	s_cmpk_gt_u32 s51, 0x55
	s_mov_b64 s[4:5], s[6:7]
	s_cbranch_scc0 .LBB0_755
	s_and_b64 vcc, exec, s[18:19]
	s_cbranch_vccz .LBB0_758
	s_barrier

.LBB0_888:
	s_add_u32 s38, s16, s30
	s_addc_u32 s39, s17, s31
	s_add_u32 s38, s38, 0x100
	s_addc_u32 s39, s39, 0
	s_add_u32 s54, s50, s30
	s_addc_u32 s55, s51, s31
	s_add_i32 s56, 0, 0x10000
	s_cmpk_eq_i32 s30, 0xf00
	s_cselect_b32 s41, s29, s39
	s_cselect_b32 s40, s28, s38
	s_cselect_b32 s39, s21, s55
	s_cselect_b32 s38, s52, s54
	s_add_i32 s57, 0, 0x14000
	v_add_u32_e32 v146, s56, v178
	v_add_u32_e32 v172, s57, v178
	ds_read_b128 v[134:137], v146
	ds_read_b128 v[138:141], v146 offset:1024
	ds_read_b128 v[142:145], v146 offset:2048
	ds_read_b128 v[146:149], v146 offset:3072
	ds_read_b128 v[150:153], v172
	ds_read_b128 v[154:157], v172 offset:1024
	ds_read_b128 v[158:161], v172 offset:2048
	ds_read_b128 v[172:175], v172 offset:3072
	v_lshl_add_u64 v[212:213], v[130:131], 0, s[30:31]
	s_add_i32 m0, s24, 0xc000
	ds_read_b128 v[180:183], v179
	ds_read_b128 v[184:187], v179 offset:1024
	ds_read_b128 v[188:191], v179 offset:2048
	ds_read_b128 v[192:195], v179 offset:3072
	ds_read_b128 v[196:199], v179 offset:4096
	ds_read_b128 v[200:203], v179 offset:5120
	ds_read_b128 v[204:207], v179 offset:6144
	ds_read_b128 v[208:211], v179 offset:7168
	global_load_lds_dwordx4 v[212:213], off
	v_lshl_add_u64 v[212:213], v[132:133], 0, s[30:31]
	s_add_i32 m0, s24, 0xe000
	s_nop 0
	global_load_lds_dwordx4 v[212:213], off
	s_waitcnt vmcnt(8)
	s_waitcnt lgkmcnt(0)
	s_barrier
	s_setprio 1
	v_mfma_f32_16x16x32_bf16 v[82:85], v[134:137], v[180:183], v[82:85]
	v_mfma_f32_16x16x32_bf16 v[82:85], v[138:141], v[184:187], v[82:85]
	v_mfma_f32_16x16x32_bf16 v[78:81], v[146:149], v[184:187], v[78:81]
	v_mfma_f32_16x16x32_bf16 v[78:81], v[142:145], v[180:183], v[78:81]
	v_mfma_f32_16x16x32_bf16 v[50:53], v[150:153], v[180:183], v[50:53]
	v_mfma_f32_16x16x32_bf16 v[50:53], v[154:157], v[184:187], v[50:53]
	v_mfma_f32_16x16x32_bf16 v[46:49], v[172:175], v[184:187], v[46:49]
	v_mfma_f32_16x16x32_bf16 v[46:49], v[158:161], v[180:183], v[46:49]
	v_mfma_f32_16x16x32_bf16 v[38:41], v[158:161], v[188:191], v[38:41]
	v_mfma_f32_16x16x32_bf16 v[38:41], v[172:175], v[192:195], v[38:41]
	v_mfma_f32_16x16x32_bf16 v[70:73], v[146:149], v[192:195], v[70:73]
	v_mfma_f32_16x16x32_bf16 v[70:73], v[142:145], v[188:191], v[70:73]
	v_mfma_f32_16x16x32_bf16 v[74:77], v[134:137], v[188:191], v[74:77]
	v_mfma_f32_16x16x32_bf16 v[74:77], v[138:141], v[192:195], v[74:77]
	v_mfma_f32_16x16x32_bf16 v[42:45], v[154:157], v[192:195], v[42:45]
	v_mfma_f32_16x16x32_bf16 v[42:45], v[150:153], v[188:191], v[42:45]
	v_mfma_f32_16x16x32_bf16 v[34:37], v[150:153], v[196:199], v[34:37]
	v_mfma_f32_16x16x32_bf16 v[34:37], v[154:157], v[200:203], v[34:37]
	v_mfma_f32_16x16x32_bf16 v[66:69], v[138:141], v[200:203], v[66:69]
	v_mfma_f32_16x16x32_bf16 v[66:69], v[134:137], v[196:199], v[66:69]
	v_mfma_f32_16x16x32_bf16 v[62:65], v[142:145], v[196:199], v[62:65]
	v_mfma_f32_16x16x32_bf16 v[62:65], v[146:149], v[200:203], v[62:65]
	v_mfma_f32_16x16x32_bf16 v[28:31], v[172:175], v[200:203], v[28:31]
	v_mfma_f32_16x16x32_bf16 v[28:31], v[158:161], v[196:199], v[28:31]
	v_mfma_f32_16x16x32_bf16 v[20:23], v[158:161], v[204:207], v[20:23]
	v_mfma_f32_16x16x32_bf16 v[20:23], v[172:175], v[208:211], v[20:23]
	v_mfma_f32_16x16x32_bf16 v[54:57], v[146:149], v[208:211], v[54:57]
	v_mfma_f32_16x16x32_bf16 v[54:57], v[142:145], v[204:207], v[54:57]
	v_mfma_f32_16x16x32_bf16 v[58:61], v[134:137], v[204:207], v[58:61]
	v_mfma_f32_16x16x32_bf16 v[58:61], v[138:141], v[208:211], v[58:61]
	v_mfma_f32_16x16x32_bf16 v[24:27], v[154:157], v[208:211], v[24:27]
	v_mfma_f32_16x16x32_bf16 v[24:27], v[150:153], v[204:207], v[24:27]
	s_setprio 0
	s_barrier
	s_add_i32 s54, s56, s13
	v_lshl_add_u64 v[212:213], s[38:39], 0, v[32:33]
	s_mov_b32 m0, s54
	ds_read_b128 v[180:183], v179 offset:16384
	ds_read_b128 v[184:187], v179 offset:17408
	ds_read_b128 v[188:191], v179 offset:18432
	ds_read_b128 v[192:195], v179 offset:19456
	ds_read_b128 v[196:199], v179 offset:20480
	ds_read_b128 v[200:203], v179 offset:21504
	ds_read_b128 v[204:207], v179 offset:22528
	ds_read_b128 v[208:211], v179 offset:23552
	global_load_lds_dwordx4 v[212:213], off
	s_add_i32 m0, s54, 0x2000
	s_add_u32 s54, s38, 0x80000
	v_lshl_add_u64 v[214:215], s[38:39], 0, v[166:167]
	s_addc_u32 s55, s39, 0
	s_add_i32 s56, s57, s13
	global_load_lds_dwordx4 v[214:215], off
	s_mov_b32 m0, s56
	v_lshl_add_u64 v[220:221], s[40:41], 0, v[164:165]
	global_load_lds_dwordx4 v32, s[54:55]
	s_add_i32 m0, s56, 0x2000
	s_nop 0
	global_load_lds_dwordx4 v166, s[54:55]
	v_lshl_add_u64 v[216:217], s[40:41], 0, v[162:163]
	s_mov_b32 m0, s24
	s_nop 0
	global_load_lds_dwordx4 v[216:217], off
	s_mov_b32 m0, s25
	s_nop 0
	global_load_lds_dwordx4 v[220:221], off
	s_waitcnt vmcnt(8)
	s_waitcnt lgkmcnt(0)
	s_barrier
	s_setprio 1
	v_mfma_f32_16x16x32_bf16 v[16:19], v[134:137], v[180:183], v[16:19]
	v_mfma_f32_16x16x32_bf16 v[16:19], v[138:141], v[184:187], v[16:19]
	v_mfma_f32_16x16x32_bf16 v[12:15], v[146:149], v[184:187], v[12:15]
	v_mfma_f32_16x16x32_bf16 v[12:15], v[142:145], v[180:183], v[12:15]
	v_mfma_f32_16x16x32_bf16 v[98:101], v[150:153], v[180:183], v[98:101]
	v_mfma_f32_16x16x32_bf16 v[98:101], v[154:157], v[184:187], v[98:101]
	v_mfma_f32_16x16x32_bf16 v[102:105], v[172:175], v[184:187], v[102:105]
	v_mfma_f32_16x16x32_bf16 v[102:105], v[158:161], v[180:183], v[102:105]
	v_mfma_f32_16x16x32_bf16 v[110:113], v[158:161], v[188:191], v[110:113]
	v_mfma_f32_16x16x32_bf16 v[110:113], v[172:175], v[192:195], v[110:113]
	v_mfma_f32_16x16x32_bf16 v[4:7], v[146:149], v[192:195], v[4:7]
	v_mfma_f32_16x16x32_bf16 v[4:7], v[142:145], v[188:191], v[4:7]
	v_mfma_f32_16x16x32_bf16 v[8:11], v[134:137], v[188:191], v[8:11]
	v_mfma_f32_16x16x32_bf16 v[8:11], v[138:141], v[192:195], v[8:11]
	v_mfma_f32_16x16x32_bf16 v[106:109], v[154:157], v[192:195], v[106:109]
	v_mfma_f32_16x16x32_bf16 v[106:109], v[150:153], v[188:191], v[106:109]
	v_mfma_f32_16x16x32_bf16 v[114:117], v[150:153], v[196:199], v[114:117]
	v_mfma_f32_16x16x32_bf16 v[114:117], v[154:157], v[200:203], v[114:117]
	v_mfma_f32_16x16x32_bf16 v[0:3], v[138:141], v[200:203], v[0:3]
	v_mfma_f32_16x16x32_bf16 v[0:3], v[134:137], v[196:199], v[0:3]
	v_mfma_f32_16x16x32_bf16 v[86:89], v[142:145], v[196:199], v[86:89]
	v_mfma_f32_16x16x32_bf16 v[86:89], v[146:149], v[200:203], v[86:89]
	v_mfma_f32_16x16x32_bf16 v[118:121], v[172:175], v[200:203], v[118:121]
	v_mfma_f32_16x16x32_bf16 v[118:121], v[158:161], v[196:199], v[118:121]
	v_mfma_f32_16x16x32_bf16 v[126:129], v[158:161], v[204:207], v[126:129]
	v_mfma_f32_16x16x32_bf16 v[126:129], v[172:175], v[208:211], v[126:129]
	v_mfma_f32_16x16x32_bf16 v[94:97], v[146:149], v[208:211], v[94:97]
	v_mfma_f32_16x16x32_bf16 v[94:97], v[142:145], v[204:207], v[94:97]
	v_mfma_f32_16x16x32_bf16 v[90:93], v[134:137], v[204:207], v[90:93]
	v_mfma_f32_16x16x32_bf16 v[90:93], v[138:141], v[208:211], v[90:93]
	v_mfma_f32_16x16x32_bf16 v[122:125], v[154:157], v[208:211], v[122:125]
	v_mfma_f32_16x16x32_bf16 v[122:125], v[150:153], v[204:207], v[122:125]
	s_setprio 0
	s_barrier
	s_add_i32 s54, 0, 0x18000
	s_add_i32 s55, 0, 0x1c000
	v_add_u32_e32 v146, s54, v178
	v_add_u32_e32 v172, s55, v178
	ds_read_b128 v[134:137], v146
	ds_read_b128 v[138:141], v146 offset:1024
	ds_read_b128 v[142:145], v146 offset:2048
	ds_read_b128 v[146:149], v146 offset:3072
	ds_read_b128 v[150:153], v172
	ds_read_b128 v[154:157], v172 offset:1024
	ds_read_b128 v[158:161], v172 offset:2048
	ds_read_b128 v[172:175], v172 offset:3072
	s_add_u32 s40, s40, 0x80000
	s_addc_u32 s41, s41, 0
	s_mov_b32 m0, s33
	ds_read_b128 v[180:183], v179 offset:32768
	ds_read_b128 v[184:187], v179 offset:33792
	ds_read_b128 v[188:191], v179 offset:34816
	ds_read_b128 v[192:195], v179 offset:35840
	ds_read_b128 v[196:199], v179 offset:36864
	ds_read_b128 v[200:203], v179 offset:37888
	ds_read_b128 v[204:207], v179 offset:38912
	ds_read_b128 v[208:211], v179 offset:39936
	global_load_lds_dwordx4 v162, s[40:41]
	s_mov_b32 m0, s36
	s_nop 0
	global_load_lds_dwordx4 v164, s[40:41]
	s_waitcnt vmcnt(8)
	s_waitcnt lgkmcnt(0)
	s_barrier
	s_setprio 1
	v_mfma_f32_16x16x32_bf16 v[82:85], v[134:137], v[180:183], v[82:85]
	v_mfma_f32_16x16x32_bf16 v[82:85], v[138:141], v[184:187], v[82:85]
	v_mfma_f32_16x16x32_bf16 v[78:81], v[146:149], v[184:187], v[78:81]
	v_mfma_f32_16x16x32_bf16 v[78:81], v[142:145], v[180:183], v[78:81]
	v_mfma_f32_16x16x32_bf16 v[50:53], v[150:153], v[180:183], v[50:53]
	v_mfma_f32_16x16x32_bf16 v[50:53], v[154:157], v[184:187], v[50:53]
	v_mfma_f32_16x16x32_bf16 v[46:49], v[172:175], v[184:187], v[46:49]
	v_mfma_f32_16x16x32_bf16 v[46:49], v[158:161], v[180:183], v[46:49]
	v_mfma_f32_16x16x32_bf16 v[38:41], v[158:161], v[188:191], v[38:41]
	v_mfma_f32_16x16x32_bf16 v[38:41], v[172:175], v[192:195], v[38:41]
	v_mfma_f32_16x16x32_bf16 v[70:73], v[146:149], v[192:195], v[70:73]
	v_mfma_f32_16x16x32_bf16 v[70:73], v[142:145], v[188:191], v[70:73]
	v_mfma_f32_16x16x32_bf16 v[74:77], v[134:137], v[188:191], v[74:77]
	v_mfma_f32_16x16x32_bf16 v[74:77], v[138:141], v[192:195], v[74:77]
	v_mfma_f32_16x16x32_bf16 v[42:45], v[154:157], v[192:195], v[42:45]
	v_mfma_f32_16x16x32_bf16 v[42:45], v[150:153], v[188:191], v[42:45]
	v_mfma_f32_16x16x32_bf16 v[34:37], v[150:153], v[196:199], v[34:37]
	v_mfma_f32_16x16x32_bf16 v[34:37], v[154:157], v[200:203], v[34:37]
	v_mfma_f32_16x16x32_bf16 v[66:69], v[138:141], v[200:203], v[66:69]
	v_mfma_f32_16x16x32_bf16 v[66:69], v[134:137], v[196:199], v[66:69]
	v_mfma_f32_16x16x32_bf16 v[62:65], v[142:145], v[196:199], v[62:65]
	v_mfma_f32_16x16x32_bf16 v[62:65], v[146:149], v[200:203], v[62:65]
	v_mfma_f32_16x16x32_bf16 v[28:31], v[172:175], v[200:203], v[28:31]
	v_mfma_f32_16x16x32_bf16 v[28:31], v[158:161], v[196:199], v[28:31]
	v_mfma_f32_16x16x32_bf16 v[20:23], v[158:161], v[204:207], v[20:23]
	v_mfma_f32_16x16x32_bf16 v[20:23], v[172:175], v[208:211], v[20:23]
	v_mfma_f32_16x16x32_bf16 v[54:57], v[146:149], v[208:211], v[54:57]
	v_mfma_f32_16x16x32_bf16 v[54:57], v[142:145], v[204:207], v[54:57]
	v_mfma_f32_16x16x32_bf16 v[58:61], v[134:137], v[204:207], v[58:61]
	v_mfma_f32_16x16x32_bf16 v[58:61], v[138:141], v[208:211], v[58:61]
	v_mfma_f32_16x16x32_bf16 v[24:27], v[154:157], v[208:211], v[24:27]
	v_mfma_f32_16x16x32_bf16 v[24:27], v[150:153], v[204:207], v[24:27]
	s_setprio 0
	s_barrier
	s_add_i32 s40, s54, s13
	v_lshl_add_u64 v[212:213], v[212:213], 0, s[34:35]
	s_mov_b32 m0, s40
	ds_read_b128 v[180:183], v179 offset:49152
	ds_read_b128 v[184:187], v179 offset:50176
	ds_read_b128 v[188:191], v179 offset:51200
	ds_read_b128 v[192:195], v179 offset:52224
	ds_read_b128 v[196:199], v179 offset:53248
	ds_read_b128 v[200:203], v179 offset:54272
	ds_read_b128 v[204:207], v179 offset:55296
	ds_read_b128 v[208:211], v179 offset:56320
	global_load_lds_dwordx4 v[212:213], off
	s_add_i32 m0, s40, 0x2000
	s_add_u32 s38, s38, 0x80080
	v_lshl_add_u64 v[212:213], v[214:215], 0, s[34:35]
	s_addc_u32 s39, s39, 0
	s_add_i32 s40, s55, s13
	global_load_lds_dwordx4 v[212:213], off
	s_mov_b32 m0, s40
	s_nop 0
	global_load_lds_dwordx4 v32, s[38:39]
	s_add_i32 m0, s40, 0x2000
	s_nop 0
	global_load_lds_dwordx4 v166, s[38:39]
	v_lshl_add_u64 v[212:213], v[216:217], 0, s[34:35]
	s_mov_b32 m0, s43
	s_nop 0
	global_load_lds_dwordx4 v[212:213], off
	v_lshl_add_u64 v[212:213], v[220:221], 0, s[34:35]
	s_mov_b32 m0, s44
	s_nop 0
	global_load_lds_dwordx4 v[212:213], off
	s_waitcnt vmcnt(8)
	s_waitcnt lgkmcnt(0)
	s_barrier
	s_setprio 1
	v_mfma_f32_16x16x32_bf16 v[16:19], v[134:137], v[180:183], v[16:19]
	v_mfma_f32_16x16x32_bf16 v[16:19], v[138:141], v[184:187], v[16:19]
	v_mfma_f32_16x16x32_bf16 v[12:15], v[146:149], v[184:187], v[12:15]
	v_mfma_f32_16x16x32_bf16 v[12:15], v[142:145], v[180:183], v[12:15]
	v_mfma_f32_16x16x32_bf16 v[98:101], v[150:153], v[180:183], v[98:101]
	v_mfma_f32_16x16x32_bf16 v[98:101], v[154:157], v[184:187], v[98:101]
	v_mfma_f32_16x16x32_bf16 v[102:105], v[172:175], v[184:187], v[102:105]
	v_mfma_f32_16x16x32_bf16 v[102:105], v[158:161], v[180:183], v[102:105]
	v_mfma_f32_16x16x32_bf16 v[110:113], v[158:161], v[188:191], v[110:113]
	v_mfma_f32_16x16x32_bf16 v[110:113], v[172:175], v[192:195], v[110:113]
	v_mfma_f32_16x16x32_bf16 v[4:7], v[146:149], v[192:195], v[4:7]
	v_mfma_f32_16x16x32_bf16 v[4:7], v[142:145], v[188:191], v[4:7]
	v_mfma_f32_16x16x32_bf16 v[8:11], v[134:137], v[188:191], v[8:11]
	v_mfma_f32_16x16x32_bf16 v[8:11], v[138:141], v[192:195], v[8:11]
	v_mfma_f32_16x16x32_bf16 v[106:109], v[154:157], v[192:195], v[106:109]
	v_mfma_f32_16x16x32_bf16 v[106:109], v[150:153], v[188:191], v[106:109]
	v_mfma_f32_16x16x32_bf16 v[114:117], v[150:153], v[196:199], v[114:117]
	v_mfma_f32_16x16x32_bf16 v[114:117], v[154:157], v[200:203], v[114:117]
	v_mfma_f32_16x16x32_bf16 v[0:3], v[138:141], v[200:203], v[0:3]
	v_mfma_f32_16x16x32_bf16 v[0:3], v[134:137], v[196:199], v[0:3]
	v_mfma_f32_16x16x32_bf16 v[86:89], v[142:145], v[196:199], v[86:89]
	v_mfma_f32_16x16x32_bf16 v[86:89], v[146:149], v[200:203], v[86:89]
	v_mfma_f32_16x16x32_bf16 v[118:121], v[172:175], v[200:203], v[118:121]
	v_mfma_f32_16x16x32_bf16 v[118:121], v[158:161], v[196:199], v[118:121]
	v_mfma_f32_16x16x32_bf16 v[126:129], v[158:161], v[204:207], v[126:129]
	v_mfma_f32_16x16x32_bf16 v[126:129], v[172:175], v[208:211], v[126:129]
	v_mfma_f32_16x16x32_bf16 v[94:97], v[146:149], v[208:211], v[94:97]
	v_mfma_f32_16x16x32_bf16 v[94:97], v[142:145], v[204:207], v[94:97]
	v_mfma_f32_16x16x32_bf16 v[90:93], v[134:137], v[204:207], v[90:93]
	v_mfma_f32_16x16x32_bf16 v[90:93], v[138:141], v[208:211], v[90:93]
	v_mfma_f32_16x16x32_bf16 v[122:125], v[154:157], v[208:211], v[122:125]
	v_mfma_f32_16x16x32_bf16 v[122:125], v[150:153], v[204:207], v[122:125]
	s_setprio 0
	s_barrier
	s_add_i32 s53, s53, 2
	s_add_u32 s30, s30, 0x100
	s_addc_u32 s31, s31, 0
	s_cmp_gt_u32 s53, 29
	s_cbranch_scc0 .LBB0_888
	s_and_b64 vcc, exec, s[18:19]
	s_cbranch_vccz .LBB0_891
	s_barrier
